# attention loop: last two PV MFMAs of each step deferred past the end-of-step barrier to cover next tile K-fragment LDS latency
# speedup vs baseline: 1.0073x; 1.0057x over previous
; #define SBAR() __builtin_amdgcn_sched_barrier(0)
; template <int I> __device__ __forceinline__ void fs_chunk(f32x16& p0, f32x16& p1, float alpha, float& l_reg, SMState& st, bf16x8& pa0, bf16x8& pa1, bf16x8& pa2, bf16x8& pa3) {
;     ...
;   if constexpr (I < 4) {
; #pragma unroll
;     for (int r = 4 * I; r < 4 * I + 4; ++r) p1[r] = __builtin_amdgcn_exp2f(p1[r]);
;     if constexpr (I == 0) st.ps = 0.f;
;   } else if constexpr (I < 8) { constexpr int j = 4 * (I - 4);
; #pragma unroll
;     for (int r = j; r < j + 4; ++r) st.ps += p0[r];
; #pragma unroll
;     for (int r = j; r < j + 4; ++r) st.ps += p1[r];
;   } else if constexpr (I == 8) {
;     const float ps_ = st.ps;
;     auto rr = __builtin_amdgcn_permlane32_swap(__float_as_uint(ps_), __float_as_uint(ps_), false, false);
;     l_reg = l_reg * alpha + (__uint_as_float(rr[0]) + __uint_as_float(rr[1]));
;     PK4(p0, 0, pa0);
;   } else if constexpr (I == 9) { PK4(p0, 8, pa1); }
;   else if constexpr (I == 10) { PK4(p1, 0, pa2); }
;   else { PK4(p1, 8, pa3); }
;     ...
; }
; template <int P> __device__ __forceinline__ void dma_piece(const DmaCtx& c) {
;   if constexpr (P < 3) __builtin_amdgcn_raw_ptr_buffer_load_lds(c.srd, (lds_u32_t*)(c.kd + (c.wid + 8 * P) * 1024), 16, c.koff[P], c.gk, 0, 0);
;   else __builtin_amdgcn_raw_ptr_buffer_load_lds(c.srd, (lds_u32_t*)(c.vd + (c.wid + 8 * (P - 3)) * 1024), 16, c.voff[P - 3], c.gv, 0, 0);
; }
; template <int D0> __device__ __forceinline__ void h1_stage(f32x16& pc0, f32x16& pc1, f32x16& pp0, f32x16& pp1, float alP, float& l_reg, SMState& st, bf16x8& pa0, bf16x8& pa1, bf16x8& pa2, bf16x8& pa3, ...
;   bf16x8 m0, m1, mq;
;   if constexpr (D0 < 10) kq_load<D0 + 2>(m0, m1, mq, Ks, qr, qlds, kb);
;   pc0 = __builtin_amdgcn_mfma_f32_32x32x16_bf16(b0, q, pc0, 0, 0, 0);
;   pc1 = __builtin_amdgcn_mfma_f32_32x32x16_bf16(b1, q, pc1, 0, 0, 0);
;   if constexpr (D0 >= 1 && D0 <= 5) dma_piece<D0 - 1>(dc);
;   SBAR(); fs_chunk<D0>(pp0, pp1, alP, l_reg, st, pa0, pa1, pa2, pa3); SBAR();
;   if constexpr (D0 < 11) h1_stage<D0 + 1>(pc0, pc1, pp0, pp1, alP, l_reg, st, pa0, pa1, pa2, pa3, n0, n1, nq, m0, m1, mq, Ks, qr, qlds, kb, dc);
.LBB0_655:
	s_add_i32 s10, s73, 1
	s_cmp_lg_u32 s73, 2
	s_cselect_b32 s52, s10, 0
	s_mul_i32 s10, s73, 0x6000
	v_add_u32_e32 v203, s10, v193
	ds_read_b128 v[204:207], v203 offset:32768
	ds_read_b128 v[208:211], v203 offset:45056
.Lattn_m2:
	v_xor_b32_e32 v112, 0x80000000, v191
	v_mov_b32_e32 v113, v112
	v_mov_b32_e32 v114, v112
	v_mov_b32_e32 v115, v112
	v_mov_b32_e32 v116, v112
	v_mov_b32_e32 v117, v112
	v_mov_b32_e32 v118, v112
	v_mov_b32_e32 v119, v112
	v_mov_b32_e32 v120, v112
	v_mov_b32_e32 v121, v112
	v_mov_b32_e32 v122, v112
	v_mov_b32_e32 v123, v112
	v_mov_b32_e32 v124, v112
	v_mov_b32_e32 v125, v112
	v_mov_b32_e32 v126, v112
	v_mov_b32_e32 v127, v112
	v_add_u32_e32 v224, s10, v199
	v_add_u32_e32 v225, s10, v200
	s_waitcnt lgkmcnt(1)
	v_mfma_f32_32x32x16_bf16 v[96:111], v[204:207], v[156:159], v[112:127]
	ds_read_b128 v[204:207], v224 offset:32768
	ds_read_b128 v[212:215], v224 offset:45056
	ds_read_b128 v[216:219], v225 offset:32768
	ds_read_b128 v[220:223], v225 offset:45056
	s_mul_i32 s11, s52, 0x6000
	s_add_i32 s53, s11, 0
	s_add_i32 s11, s51, 0xfffbe000
	s_waitcnt lgkmcnt(4)
	v_mfma_f32_32x32x16_bf16 v[112:127], v[208:211], v[156:159], v[112:127]
	v_exp_f32_e32 v226, v80
	v_exp_f32_e32 v227, v81
	v_exp_f32_e32 v228, v82
	v_exp_f32_e32 v229, v83
	v_add_u32_e32 v230, s10, v201
	s_add_i32 s10, s53, s69
	s_add_i32 m0, s10, 0x8000
	ds_read_b128 v[80:83], v230 offset:32768
	ds_read_b128 v[208:211], v230 offset:45056
	buffer_load_dwordx4 v194, s[28:31], s51 offen lds
	s_waitcnt lgkmcnt(5)
	v_mfma_f32_32x32x16_bf16 v[96:111], v[204:207], v[152:155], v[96:111]
	s_waitcnt lgkmcnt(4)
	v_mfma_f32_32x32x16_bf16 v[112:127], v[212:215], v[152:155], v[112:127]
	v_exp_f32_e32 v231, v84
	v_exp_f32_e32 v232, v85
	v_exp_f32_e32 v233, v86
	v_exp_f32_e32 v234, v87
	s_add_i32 m0, s10, 0xa000
	ds_read_b128 v[84:87], v203 offset:32896
	ds_read_b128 v[204:207], v203 offset:45184
	buffer_load_dwordx4 v195, s[28:31], s51 offen lds
	s_waitcnt lgkmcnt(5)
	v_mfma_f32_32x32x16_bf16 v[96:111], v[216:219], v[148:151], v[96:111]
	s_waitcnt lgkmcnt(4)
	v_mfma_f32_32x32x16_bf16 v[112:127], v[220:223], v[148:151], v[112:127]
	v_exp_f32_e32 v235, v88
	v_exp_f32_e32 v236, v89
	v_exp_f32_e32 v237, v90
	v_exp_f32_e32 v238, v91
	s_add_i32 m0, s10, 0xc000
	ds_read_b128 v[88:91], v224 offset:32896
	ds_read_b128 v[212:215], v224 offset:45184
	buffer_load_dwordx4 v196, s[28:31], s51 offen lds
	s_waitcnt lgkmcnt(5)
	v_mfma_f32_32x32x16_bf16 v[96:111], v[80:83], v[144:147], v[96:111]
	s_waitcnt lgkmcnt(4)
	v_mfma_f32_32x32x16_bf16 v[112:127], v[208:211], v[144:147], v[112:127]
	v_exp_f32_e32 v239, v92
	v_exp_f32_e32 v240, v93
	v_exp_f32_e32 v241, v94
	v_exp_f32_e32 v242, v95
	s_mov_b32 m0, s50
	ds_read_b128 v[80:83], v225 offset:32896
	ds_read_b128 v[92:95], v225 offset:45184
	buffer_load_dwordx4 v197, s[28:31], s11 offen lds
	s_waitcnt lgkmcnt(5)
	v_mfma_f32_32x32x16_bf16 v[96:111], v[84:87], v[140:143], v[96:111]
	s_waitcnt lgkmcnt(4)
	v_mfma_f32_32x32x16_bf16 v[112:127], v[204:207], v[140:143], v[112:127]
	v_add_f32_e32 v84, 0, v64
	v_add_f32_e32 v84, v65, v84
	v_add_f32_e32 v84, v66, v84
	v_add_f32_e32 v84, v67, v84
	v_add_f32_e32 v84, v226, v84
	v_add_f32_e32 v84, v227, v84
	v_add_f32_e32 v84, v228, v84
	v_add_f32_e32 v208, v229, v84
	s_mov_b32 m0, s49
	ds_read_b128 v[84:87], v230 offset:32896
	ds_read_b128 v[204:207], v230 offset:45184
	buffer_load_dwordx4 v198, s[28:31], s11 offen lds
	s_waitcnt lgkmcnt(5)
	v_mfma_f32_32x32x16_bf16 v[96:111], v[88:91], v[136:139], v[96:111]
	s_waitcnt lgkmcnt(4)
	v_mfma_f32_32x32x16_bf16 v[112:127], v[212:215], v[136:139], v[112:127]
	v_add_f32_e32 v88, v68, v208
	v_add_f32_e32 v88, v69, v88
	v_add_f32_e32 v88, v70, v88
	v_add_f32_e32 v88, v71, v88
	v_add_f32_e32 v88, v231, v88
	v_add_f32_e32 v88, v232, v88
	v_add_f32_e32 v88, v233, v88
	v_add_f32_e32 v212, v234, v88
	s_waitcnt lgkmcnt(3)
	v_mfma_f32_32x32x16_bf16 v[96:111], v[80:83], v[132:135], v[96:111]
	ds_read_b128 v[80:83], v203 offset:45312
	ds_read_b128 v[88:91], v203 offset:33024
	ds_read_b128 v[208:211], v192
	s_waitcnt lgkmcnt(5)
	v_mfma_f32_32x32x16_bf16 v[112:127], v[92:95], v[132:135], v[112:127]
	v_add_f32_e32 v92, v72, v212
	v_add_f32_e32 v92, v73, v92
	v_add_f32_e32 v92, v74, v92
	v_add_f32_e32 v92, v75, v92
	v_add_f32_e32 v92, v235, v92
	v_add_f32_e32 v92, v236, v92
	v_add_f32_e32 v92, v237, v92
	v_add_f32_e32 v203, v238, v92
	s_waitcnt lgkmcnt(4)
	v_mfma_f32_32x32x16_bf16 v[96:111], v[84:87], v[128:131], v[96:111]
	ds_read_b128 v[84:87], v224 offset:45312
	ds_read_b128 v[92:95], v224 offset:33024
	ds_read_b128 v[212:215], v192 offset:1024
	s_waitcnt lgkmcnt(6)
	v_mfma_f32_32x32x16_bf16 v[112:127], v[204:207], v[128:131], v[112:127]
	v_add_f32_e32 v203, v76, v203
	v_add_f32_e32 v203, v77, v203
	v_add_f32_e32 v203, v78, v203
	v_add_f32_e32 v203, v79, v203
	v_add_f32_e32 v203, v239, v203
	v_add_f32_e32 v203, v240, v203
	v_add_f32_e32 v203, v241, v203
	v_add_f32_e32 v203, v242, v203
	s_waitcnt lgkmcnt(3)
	v_mfma_f32_32x32x16_bf16 v[96:111], v[88:91], v[208:211], v[96:111]
	ds_read_b128 v[88:91], v225 offset:45312
	ds_read_b128 v[216:219], v225 offset:33024
	ds_read_b128 v[220:223], v192 offset:2048
	v_mfma_f32_32x32x16_bf16 v[112:127], v[80:83], v[208:211], v[112:127]
	v_mov_b32_e32 v204, v203
	v_cvt_pk_bf16_f32 v80, v64, v65
	v_cvt_pk_bf16_f32 v81, v66, v67
	v_cvt_pk_bf16_f32 v82, v68, v69
	v_cvt_pk_bf16_f32 v83, v70, v71
	v_permlane32_swap_b32_e32 v203, v204
	v_permlane32_swap_b32_e32 v80, v82
	v_permlane32_swap_b32_e32 v81, v83
	s_waitcnt lgkmcnt(3)
; template <int I> __device__ __forceinline__ void ps_chunk(f32x16& p0, f32x16& p1, float& M, float& alpha, SMState& st) {
;   if constexpr (I == 0) { float m = p0[0];
; #pragma unroll
;     for (int r = 1; r < 16; ++r) m = fmaxf(m, p0[r]);
;     st.pmax = m;
;   } else if constexpr (I == 1) { float m = st.pmax;
; #pragma unroll
;     for (int r = 0; r < 16; ++r) m = fmaxf(m, p1[r]);
;     auto rr = __builtin_amdgcn_permlane32_swap(__float_as_uint(m), __float_as_uint(m), false, false);
;     st.pmax = fmaxf(__uint_as_float(rr[0]), __uint_as_float(rr[1]));
;   } else if constexpr (I == 2) {
;     alpha = 1.f;
;     if (__builtin_expect(!__all(st.pmax <= THR2), 0)) { const float d = fmaxf(st.pmax, 0.f); M += d; alpha = __builtin_amdgcn_exp2f(-d);
; #pragma unroll
;       for (int r = 0; r < 16; ++r) { p0[r] -= d; p1[r] -= d; } }
; #pragma unroll
;     for (int r = 0; r < 2; ++r) p0[r] = __builtin_amdgcn_exp2f(p0[r]);
;   } else if constexpr (I < 7) { constexpr int lo = 2 + 3 * (I - 3), hi_ = lo + 3;
; #pragma unroll
;     for (int r = lo; r < hi_; ++r) p0[r] = __builtin_amdgcn_exp2f(p0[r]);
;   } else {
; #pragma unroll
;     for (int r = 14; r < 16; ++r) p0[r] = __builtin_amdgcn_exp2f(p0[r]);
;   }
;   if constexpr (I >= 2) asm volatile("" : "+v"(p0), "+v"(p1));
; }
; template <int G> __device__ __forceinline__ void v_load(s16x4& la, s16x4& ha, s16x4& lb, s16x4& hb, const __attribute__((address_space(3))) char* vb) {
;   constexpr int ks = G >> 1, d0 = (G & 1) * 2;
;   la = __builtin_amdgcn_ds_read_tr16_b64_v4i16((lds_s16x4b*)(vb + v_rd_off(d0, ks, 0))); ha = __builtin_amdgcn_ds_read_tr16_b64_v4i16((lds_s16x4b*)(vb + v_rd_off(d0, ks, 1)));
;   lb = __builtin_amdgcn_ds_read_tr16_b64_v4i16((lds_s16x4b*)(vb + v_rd_off(d0 + 1, ks, 0))); hb = __builtin_amdgcn_ds_read_tr16_b64_v4i16((lds_s16x4b*)(vb + v_rd_off(d0 + 1, ks, 1)));
; }
; template <int G> __device__ __forceinline__ void h2_stage(f32x16* o, f32x16& pc0, f32x16& pc1, float& m_reg, float& alC, SMState& st, bf16x8 pa0, bf16x8 pa1, bf16x8 pa2, bf16x8 pa3, ...
;   constexpr int ks = G >> 1, d0 = (G & 1) * 2;
;   s16x4 nla, nha, nlb, nhb;
;   if constexpr (G < 7) v_load<G + 1>(nla, nha, nlb, nhb, vb);
;   const bf16x8 pa = ks == 0 ? pa0 : ks == 1 ? pa1 : ks == 2 ? pa2 : pa3;
;     ...
;   o[d0] = __builtin_amdgcn_mfma_f32_32x32x16_bf16(pa, PK(la, ha), o[d0], 0, 0, 0);
	v_mfma_f32_32x32x16_bf16 v[96:111], v[92:95], v[212:215], v[96:111]
	ds_read_b128 v[64:67], v192 offset:3072
	ds_read_b128 v[92:95], v230 offset:33024
	ds_read_b128 v[206:209], v230 offset:45312
	v_mfma_f32_32x32x16_bf16 v[112:127], v[84:87], v[212:215], v[112:127]
	v_cvt_pk_bf16_f32 v72, v72, v73
	v_cvt_pk_bf16_f32 v73, v74, v75
	v_cvt_pk_bf16_f32 v74, v76, v77
	v_cvt_pk_bf16_f32 v75, v78, v79
	s_nop 0
	v_permlane32_swap_b32_e32 v72, v74
	v_permlane32_swap_b32_e32 v73, v75
	s_waitcnt lgkmcnt(3)
	v_mfma_f32_32x32x16_bf16 v[96:111], v[216:219], v[220:223], v[96:111]
	v_mfma_f32_32x32x16_bf16 v[112:127], v[88:91], v[220:223], v[112:127]
	v_cvt_pk_bf16_f32 v68, v226, v227
	v_cvt_pk_bf16_f32 v69, v228, v229
	v_cvt_pk_bf16_f32 v70, v231, v232
	v_cvt_pk_bf16_f32 v71, v233, v234
	s_nop 0
	v_permlane32_swap_b32_e32 v68, v70
	v_permlane32_swap_b32_e32 v69, v71
	s_waitcnt lgkmcnt(1)
	v_mfma_f32_32x32x16_bf16 v[96:111], v[92:95], v[64:67], v[96:111]
	s_waitcnt lgkmcnt(0)
	v_mfma_f32_32x32x16_bf16 v[112:127], v[206:209], v[64:67], v[112:127]
	v_cvt_pk_bf16_f32 v64, v235, v236
	v_cvt_pk_bf16_f32 v65, v237, v238
	v_cvt_pk_bf16_f32 v66, v239, v240
	v_cvt_pk_bf16_f32 v67, v241, v242
	s_nop 0
	v_permlane32_swap_b32_e32 v64, v66
	v_permlane32_swap_b32_e32 v65, v67
	ds_read_b64_tr_b16 v[78:79], v188 offset:2048
	ds_read_b64_tr_b16 v[76:77], v188
	ds_read_b64_tr_b16 v[84:85], v188 offset:512
	ds_read_b64_tr_b16 v[88:89], v188 offset:1024
	ds_read_b64_tr_b16 v[92:93], v188 offset:1536
	ds_read_b64_tr_b16 v[86:87], v188 offset:2560
	ds_read_b64_tr_b16 v[90:91], v188 offset:3072
	ds_read_b64_tr_b16 v[94:95], v188 offset:3584
	s_waitcnt lgkmcnt(6)
	v_mfma_f32_32x32x16_bf16 v[0:15], v[80:83], v[76:79], v[0:15]
	s_waitcnt lgkmcnt(2)
	v_mfma_f32_32x32x16_bf16 v[48:63], v[80:83], v[84:87], v[48:63]
	v_max_f32_e32 v76, v97, v97
	v_max_f32_e32 v77, v96, v96
	v_max_f32_e32 v76, v77, v76
	v_max3_f32 v76, v76, v98, v99
	v_max3_f32 v76, v76, v100, v101
	v_max3_f32 v76, v76, v102, v103
	v_max3_f32 v76, v76, v104, v105
	v_max3_f32 v76, v76, v106, v107
	v_max3_f32 v76, v76, v108, v109
	v_max3_f32 v84, v76, v110, v111
	s_waitcnt lgkmcnt(1)
	v_mfma_f32_32x32x16_bf16 v[32:47], v[80:83], v[88:91], v[32:47]
	ds_read_b64_tr_b16 v[76:77], v188 offset:4096
	ds_read_b64_tr_b16 v[78:79], v188 offset:6144
	ds_read_b64_tr_b16 v[88:89], v188 offset:6656
	ds_read_b64_tr_b16 v[86:87], v188 offset:4608
	s_waitcnt lgkmcnt(4)
	v_mfma_f32_32x32x16_bf16 v[16:31], v[80:83], v[92:95], v[16:31]
	v_max3_f32 v80, v84, v112, v113
	v_max3_f32 v80, v80, v114, v115
	v_max3_f32 v80, v80, v116, v117
	v_max3_f32 v80, v80, v118, v119
	v_max3_f32 v80, v80, v120, v121
	v_max3_f32 v80, v80, v122, v123
	v_max3_f32 v80, v80, v124, v125
	v_max3_f32 v80, v80, v126, v127
	v_mov_b32_e32 v81, v80
	s_nop 1
	v_permlane32_swap_b32_e32 v80, v81
	v_max_f32_e32 v81, v81, v81
	v_max_f32_e32 v80, v80, v80
	v_max_f32_e32 v84, v80, v81
	s_waitcnt lgkmcnt(2)
	v_mfma_f32_32x32x16_bf16 v[0:15], v[72:75], v[76:79], v[0:15]
	ds_read_b64_tr_b16 v[80:81], v188 offset:5120
	ds_read_b64_tr_b16 v[82:83], v188 offset:7168
	ds_read_b64_tr_b16 v[78:79], v188 offset:7680
	ds_read_b64_tr_b16 v[76:77], v188 offset:5632
	s_waitcnt lgkmcnt(4)
	v_mfma_f32_32x32x16_bf16 v[48:63], v[72:75], v[86:89], v[48:63]
	v_cmp_ge_f32_e32 vcc, s67, v84
	s_cmp_eq_u64 vcc, exec
	s_cbranch_scc0 .LBB0_668
	v_mov_b32_e32 v206, 1.0
.LBB0_657:
	v_exp_f32_e32 v96, v96
	v_exp_f32_e32 v97, v97
	s_waitcnt lgkmcnt(2)
	v_mfma_f32_32x32x16_bf16 v[32:47], v[72:75], v[80:83], v[32:47]
	ds_read_b64_tr_b16 v[80:81], v188 offset:8192
	ds_read_b64_tr_b16 v[82:83], v188 offset:10240
	ds_read_b64_tr_b16 v[86:87], v188 offset:10752
	ds_read_b64_tr_b16 v[84:85], v188 offset:8704
	s_waitcnt lgkmcnt(4)
	v_mfma_f32_32x32x16_bf16 v[16:31], v[72:75], v[76:79], v[16:31]
	v_exp_f32_e32 v98, v98
	v_exp_f32_e32 v99, v99
	v_exp_f32_e32 v100, v100
	s_waitcnt lgkmcnt(2)
	v_mfma_f32_32x32x16_bf16 v[0:15], v[68:71], v[80:83], v[0:15]
	ds_read_b64_tr_b16 v[72:73], v188 offset:9216
	ds_read_b64_tr_b16 v[74:75], v188 offset:11264
	ds_read_b64_tr_b16 v[78:79], v188 offset:11776
	ds_read_b64_tr_b16 v[76:77], v188 offset:9728
	s_waitcnt lgkmcnt(4)
	v_mfma_f32_32x32x16_bf16 v[48:63], v[68:71], v[84:87], v[48:63]
	v_exp_f32_e32 v101, v101
	v_exp_f32_e32 v102, v102
	v_exp_f32_e32 v103, v103
	s_waitcnt lgkmcnt(2)
	v_mfma_f32_32x32x16_bf16 v[32:47], v[68:71], v[72:75], v[32:47]
	ds_read_b64_tr_b16 v[72:73], v188 offset:12288
	ds_read_b64_tr_b16 v[74:75], v188 offset:14336
	ds_read_b64_tr_b16 v[82:83], v188 offset:14848
	ds_read_b64_tr_b16 v[80:81], v188 offset:12800
	s_waitcnt lgkmcnt(4)
	v_mfma_f32_32x32x16_bf16 v[16:31], v[68:71], v[76:79], v[16:31]
	v_exp_f32_e32 v104, v104
	v_exp_f32_e32 v105, v105
	v_exp_f32_e32 v106, v106
	s_waitcnt lgkmcnt(2)
	v_mfma_f32_32x32x16_bf16 v[0:15], v[64:67], v[72:75], v[0:15]
	ds_read_b64_tr_b16 v[68:69], v188 offset:13312
	ds_read_b64_tr_b16 v[70:71], v188 offset:15360
	ds_read_b64_tr_b16 v[74:75], v188 offset:15872
	ds_read_b64_tr_b16 v[72:73], v188 offset:13824
	s_waitcnt lgkmcnt(4)
	v_mfma_f32_32x32x16_bf16 v[48:63], v[64:67], v[80:83], v[48:63]
	v_exp_f32_e32 v107, v107
	v_exp_f32_e32 v108, v108
	v_exp_f32_e32 v109, v109
	s_waitcnt lgkmcnt(0)
	v_exp_f32_e32 v110, v110
	v_exp_f32_e32 v111, v111
	s_waitcnt vmcnt(0)
	v_cmp_gt_f32_e32 vcc, 1.0, v206
	s_cbranch_vccz .Lattn_n1
	v_mfma_f32_32x32x16_bf16 v[32:47], v[64:67], v[68:71], v[32:47]
	v_mfma_f32_32x32x16_bf16 v[16:31], v[64:67], v[72:75], v[16:31]
	s_nop 15
	s_nop 15
	s_and_saveexec_b64 s[10:11], s[4:5]
	ds_write_b32 v189, v206 offset:128
	s_or_b64 exec, exec, s[10:11]
	s_waitcnt lgkmcnt(0)
	v_add_u32_e32 v76, s1, v166
	ds_read_b128 v[64:67], v76 offset:224
	ds_read_b128 v[68:71], v76 offset:192
	ds_read_b128 v[72:75], v76 offset:160
	ds_read_b128 v[76:79], v76 offset:128
	s_waitcnt lgkmcnt(3)
	v_pk_mul_f32 v[12:13], v[12:13], v[64:65]
	s_waitcnt lgkmcnt(2)
	v_pk_mul_f32 v[8:9], v[8:9], v[68:69]
	s_waitcnt lgkmcnt(1)
	v_pk_mul_f32 v[4:5], v[4:5], v[72:73]
	v_pk_mul_f32 v[14:15], v[14:15], v[66:67]
	v_pk_mul_f32 v[10:11], v[10:11], v[70:71]
	v_pk_mul_f32 v[6:7], v[6:7], v[74:75]
	s_waitcnt lgkmcnt(0)
	v_pk_mul_f32 v[2:3], v[2:3], v[78:79]
	v_pk_mul_f32 v[0:1], v[0:1], v[76:77]
	v_pk_mul_f32 v[60:61], v[60:61], v[64:65]
	v_pk_mul_f32 v[56:57], v[56:57], v[68:69]
	v_pk_mul_f32 v[52:53], v[52:53], v[72:73]
	v_pk_mul_f32 v[62:63], v[62:63], v[66:67]
	v_pk_mul_f32 v[58:59], v[58:59], v[70:71]
	v_pk_mul_f32 v[54:55], v[54:55], v[74:75]
	v_pk_mul_f32 v[50:51], v[50:51], v[78:79]
	v_pk_mul_f32 v[48:49], v[48:49], v[76:77]
	v_pk_mul_f32 v[44:45], v[44:45], v[64:65]
	v_pk_mul_f32 v[40:41], v[40:41], v[68:69]
	v_pk_mul_f32 v[36:37], v[36:37], v[72:73]
	v_pk_mul_f32 v[46:47], v[46:47], v[66:67]
	v_pk_mul_f32 v[42:43], v[42:43], v[70:71]
	v_pk_mul_f32 v[38:39], v[38:39], v[74:75]
	v_pk_mul_f32 v[34:35], v[34:35], v[78:79]
	v_pk_mul_f32 v[32:33], v[32:33], v[76:77]
	v_pk_mul_f32 v[28:29], v[28:29], v[64:65]
	v_pk_mul_f32 v[24:25], v[24:25], v[68:69]
	v_pk_mul_f32 v[20:21], v[20:21], v[72:73]
	v_pk_mul_f32 v[30:31], v[30:31], v[66:67]
	v_pk_mul_f32 v[26:27], v[26:27], v[70:71]
	v_pk_mul_f32 v[22:23], v[22:23], v[74:75]
	v_pk_mul_f32 v[18:19], v[18:19], v[78:79]
	v_pk_mul_f32 v[16:17], v[16:17], v[76:77]
	s_waitcnt lgkmcnt(0)
	s_barrier
	v_add_u32_e32 v205, s53, v193
	ds_read_b128 v[208:211], v205 offset:32768
	ds_read_b128 v[212:215], v205 offset:45056
	s_branch .Lattn_m1
.Lattn_n1:
	v_add_u32_e32 v205, s53, v193
	s_waitcnt lgkmcnt(0)
	s_barrier
	ds_read_b128 v[208:211], v205 offset:32768
	ds_read_b128 v[212:215], v205 offset:45056
	v_mfma_f32_32x32x16_bf16 v[32:47], v[64:67], v[68:71], v[32:47]
	v_mfma_f32_32x32x16_bf16 v[16:31], v[64:67], v[72:75], v[16:31]
.Lattn_m1:
	v_xor_b32_e32 v80, 0x80000000, v191
	v_mov_b32_e32 v81, v80
	v_mov_b32_e32 v82, v80
	v_mov_b32_e32 v83, v80
	v_mov_b32_e32 v84, v80
	v_mov_b32_e32 v85, v80
	v_mov_b32_e32 v86, v80
	v_mov_b32_e32 v87, v80
	v_mov_b32_e32 v88, v80
	v_mov_b32_e32 v89, v80
	v_mov_b32_e32 v90, v80
	v_mov_b32_e32 v91, v80
	v_mov_b32_e32 v92, v80
	v_mov_b32_e32 v93, v80
	v_mov_b32_e32 v94, v80
	v_mov_b32_e32 v95, v80
	v_add_u32_e32 v207, s53, v199
	v_add_u32_e32 v228, s53, v200
	s_waitcnt lgkmcnt(1)
	v_mfma_f32_32x32x16_bf16 v[64:79], v[208:211], v[156:159], v[80:95]
	s_add_i32 s10, s51, 0x42000
	s_add_i32 s11, s52, 1
	ds_read_b128 v[208:211], v207 offset:32768
	ds_read_b128 v[216:219], v207 offset:45056
	ds_read_b128 v[220:223], v228 offset:32768
	ds_read_b128 v[224:227], v228 offset:45056
	s_cmp_lg_u32 s52, 2
	s_cselect_b32 s73, s11, 0
	s_mul_i32 s11, s73, 0x6000
	s_waitcnt lgkmcnt(4)
	v_mfma_f32_32x32x16_bf16 v[80:95], v[212:215], v[156:159], v[80:95]
	s_add_i32 s52, s11, 0
	v_exp_f32_e32 v229, v112
	v_exp_f32_e32 v230, v113
	v_exp_f32_e32 v231, v114
	v_exp_f32_e32 v232, v115
	s_add_i32 s11, s52, s69
	v_add_u32_e32 v233, s53, v201
	s_add_i32 m0, s11, 0x8000
	ds_read_b128 v[112:115], v233 offset:32768
	ds_read_b128 v[212:215], v233 offset:45056
	buffer_load_dwordx4 v194, s[28:31], s10 offen lds
	s_waitcnt lgkmcnt(5)
	v_mfma_f32_32x32x16_bf16 v[64:79], v[208:211], v[152:155], v[64:79]
	s_waitcnt lgkmcnt(4)
	v_mfma_f32_32x32x16_bf16 v[80:95], v[216:219], v[152:155], v[80:95]
	v_exp_f32_e32 v234, v116
	v_exp_f32_e32 v235, v117
	v_exp_f32_e32 v236, v118
	v_exp_f32_e32 v237, v119
	s_add_i32 m0, s11, 0xa000
	ds_read_b128 v[116:119], v205 offset:32896
	ds_read_b128 v[208:211], v205 offset:45184
	buffer_load_dwordx4 v195, s[28:31], s10 offen lds
	s_waitcnt lgkmcnt(5)
	v_mfma_f32_32x32x16_bf16 v[64:79], v[220:223], v[148:151], v[64:79]
	s_waitcnt lgkmcnt(4)
	v_mfma_f32_32x32x16_bf16 v[80:95], v[224:227], v[148:151], v[80:95]
	v_exp_f32_e32 v238, v120
	v_exp_f32_e32 v239, v121
	v_exp_f32_e32 v240, v122
	v_exp_f32_e32 v241, v123
	s_add_i32 m0, s11, 0xc000
	ds_read_b128 v[120:123], v207 offset:32896
	ds_read_b128 v[216:219], v207 offset:45184
	buffer_load_dwordx4 v196, s[28:31], s10 offen lds
	s_waitcnt lgkmcnt(5)
	v_mfma_f32_32x32x16_bf16 v[64:79], v[112:115], v[144:147], v[64:79]
	s_waitcnt lgkmcnt(4)
	v_mfma_f32_32x32x16_bf16 v[80:95], v[212:215], v[144:147], v[80:95]
	v_exp_f32_e32 v242, v124
	v_exp_f32_e32 v243, v125
	v_exp_f32_e32 v244, v126
	v_exp_f32_e32 v245, v127
	s_mov_b32 m0, s70
	ds_read_b128 v[112:115], v228 offset:32896
	ds_read_b128 v[124:127], v228 offset:45184
	buffer_load_dwordx4 v197, s[28:31], s51 offen lds
	s_waitcnt lgkmcnt(5)
	v_mfma_f32_32x32x16_bf16 v[64:79], v[116:119], v[140:143], v[64:79]
	s_waitcnt lgkmcnt(4)
	v_mfma_f32_32x32x16_bf16 v[80:95], v[208:211], v[140:143], v[80:95]
	v_add_f32_e32 v116, 0, v96
	v_add_f32_e32 v116, v97, v116
	v_add_f32_e32 v116, v98, v116
	v_add_f32_e32 v116, v99, v116
	v_add_f32_e32 v116, v229, v116
	v_add_f32_e32 v116, v230, v116
	v_add_f32_e32 v116, v231, v116
	v_add_f32_e32 v212, v232, v116
	s_mov_b32 m0, s71
	ds_read_b128 v[116:119], v233 offset:32896
	ds_read_b128 v[208:211], v233 offset:45184
	buffer_load_dwordx4 v198, s[28:31], s51 offen lds
	s_waitcnt lgkmcnt(5)
; template <int I> __device__ __forceinline__ void fs_chunk(f32x16& p0, f32x16& p1, float alpha, float& l_reg, SMState& st, bf16x8& pa0, bf16x8& pa1, bf16x8& pa2, bf16x8& pa3) {
;     ...
;   if constexpr (I < 4) {
; #pragma unroll
;     for (int r = 4 * I; r < 4 * I + 4; ++r) p1[r] = __builtin_amdgcn_exp2f(p1[r]);
;     if constexpr (I == 0) st.ps = 0.f;
;   } else if constexpr (I < 8) { constexpr int j = 4 * (I - 4);
; #pragma unroll
;     for (int r = j; r < j + 4; ++r) st.ps += p0[r];
; #pragma unroll
;     for (int r = j; r < j + 4; ++r) st.ps += p1[r];
;   } else if constexpr (I == 8) {
;     const float ps_ = st.ps;
;     auto rr = __builtin_amdgcn_permlane32_swap(__float_as_uint(ps_), __float_as_uint(ps_), false, false);
;     l_reg = l_reg * alpha + (__uint_as_float(rr[0]) + __uint_as_float(rr[1]));
;     PK4(p0, 0, pa0);
;   } else if constexpr (I == 9) { PK4(p0, 8, pa1); }
;   else if constexpr (I == 10) { PK4(p1, 0, pa2); }
;   else { PK4(p1, 8, pa3); }
;     ...
; }
; template <int I> __device__ __forceinline__ void ps_chunk(f32x16& p0, f32x16& p1, float& M, float& alpha, SMState& st) {
;   if constexpr (I == 0) { float m = p0[0];
; #pragma unroll
;     for (int r = 1; r < 16; ++r) m = fmaxf(m, p0[r]);
;     st.pmax = m;
;   } else if constexpr (I == 1) { float m = st.pmax;
; #pragma unroll
;     for (int r = 0; r < 16; ++r) m = fmaxf(m, p1[r]);
;     auto rr = __builtin_amdgcn_permlane32_swap(__float_as_uint(m), __float_as_uint(m), false, false);
;     st.pmax = fmaxf(__uint_as_float(rr[0]), __uint_as_float(rr[1]));
;   } else if constexpr (I == 2) {
;     alpha = 1.f;
;     if (__builtin_expect(!__all(st.pmax <= THR2), 0)) { const float d = fmaxf(st.pmax, 0.f); M += d; alpha = __builtin_amdgcn_exp2f(-d);
; #pragma unroll
;       for (int r = 0; r < 16; ++r) { p0[r] -= d; p1[r] -= d; } }
; #pragma unroll
;     for (int r = 0; r < 2; ++r) p0[r] = __builtin_amdgcn_exp2f(p0[r]);
;   } else if constexpr (I < 7) { constexpr int lo = 2 + 3 * (I - 3), hi_ = lo + 3;
; #pragma unroll
;     for (int r = lo; r < hi_; ++r) p0[r] = __builtin_amdgcn_exp2f(p0[r]);
;   } else {
; #pragma unroll
;     for (int r = 14; r < 16; ++r) p0[r] = __builtin_amdgcn_exp2f(p0[r]);
;   }
;   if constexpr (I >= 2) asm volatile("" : "+v"(p0), "+v"(p1));
; }
	v_mfma_f32_32x32x16_bf16 v[64:79], v[120:123], v[136:139], v[64:79]
	s_waitcnt lgkmcnt(4)
	v_mfma_f32_32x32x16_bf16 v[80:95], v[216:219], v[136:139], v[80:95]
	v_add_f32_e32 v120, v100, v212
	v_add_f32_e32 v120, v101, v120
	v_add_f32_e32 v120, v102, v120
	v_add_f32_e32 v120, v103, v120
	v_add_f32_e32 v120, v234, v120
	v_add_f32_e32 v120, v235, v120
	v_add_f32_e32 v120, v236, v120
	v_add_f32_e32 v216, v237, v120
	s_waitcnt lgkmcnt(3)
	v_mfma_f32_32x32x16_bf16 v[64:79], v[112:115], v[132:135], v[64:79]
	ds_read_b128 v[112:115], v205 offset:45312
	ds_read_b128 v[120:123], v205 offset:33024
	ds_read_b128 v[212:215], v192
	s_waitcnt lgkmcnt(5)
	v_mfma_f32_32x32x16_bf16 v[80:95], v[124:127], v[132:135], v[80:95]
	v_add_f32_e32 v124, v104, v216
	v_add_f32_e32 v124, v105, v124
	v_add_f32_e32 v124, v106, v124
	v_add_f32_e32 v124, v107, v124
	v_add_f32_e32 v124, v238, v124
	v_add_f32_e32 v124, v239, v124
	v_add_f32_e32 v124, v240, v124
	v_add_f32_e32 v205, v241, v124
	s_waitcnt lgkmcnt(4)
	v_mfma_f32_32x32x16_bf16 v[64:79], v[116:119], v[128:131], v[64:79]
	ds_read_b128 v[124:127], v207 offset:45312
	ds_read_b128 v[216:219], v207 offset:33024
	ds_read_b128 v[220:223], v192 offset:1024
	s_waitcnt lgkmcnt(6)
	v_mfma_f32_32x32x16_bf16 v[80:95], v[208:211], v[128:131], v[80:95]
	v_add_f32_e32 v116, v108, v205
	v_add_f32_e32 v116, v109, v116
	v_add_f32_e32 v116, v110, v116
	v_add_f32_e32 v116, v111, v116
	v_add_f32_e32 v116, v242, v116
	v_add_f32_e32 v116, v243, v116
	v_add_f32_e32 v116, v244, v116
	v_add_f32_e32 v116, v245, v116
	s_waitcnt lgkmcnt(3)
	v_mfma_f32_32x32x16_bf16 v[64:79], v[120:123], v[212:215], v[64:79]
	ds_read_b128 v[118:121], v228 offset:45312
	ds_read_b128 v[208:211], v228 offset:33024
	ds_read_b128 v[224:227], v192 offset:2048
	v_mfma_f32_32x32x16_bf16 v[80:95], v[112:115], v[212:215], v[80:95]
	v_mov_b32_e32 v117, v116
	v_cvt_pk_bf16_f32 v112, v96, v97
	v_cvt_pk_bf16_f32 v113, v98, v99
	v_cvt_pk_bf16_f32 v114, v100, v101
	v_cvt_pk_bf16_f32 v115, v102, v103
	v_permlane32_swap_b32_e32 v116, v117
	v_permlane32_swap_b32_e32 v112, v114
	v_permlane32_swap_b32_e32 v113, v115
	s_waitcnt lgkmcnt(3)
	v_mfma_f32_32x32x16_bf16 v[64:79], v[216:219], v[220:223], v[64:79]
	ds_read_b128 v[96:99], v192 offset:3072
	ds_read_b128 v[212:215], v233 offset:33024
	ds_read_b128 v[216:219], v233 offset:45312
	v_mfma_f32_32x32x16_bf16 v[80:95], v[124:127], v[220:223], v[80:95]
	v_cvt_pk_bf16_f32 v104, v104, v105
	v_cvt_pk_bf16_f32 v105, v106, v107
	v_cvt_pk_bf16_f32 v106, v108, v109
	v_cvt_pk_bf16_f32 v107, v110, v111
	s_nop 0
	v_permlane32_swap_b32_e32 v104, v106
	v_permlane32_swap_b32_e32 v105, v107
	s_waitcnt lgkmcnt(3)
	v_mfma_f32_32x32x16_bf16 v[64:79], v[208:211], v[224:227], v[64:79]
	v_mfma_f32_32x32x16_bf16 v[80:95], v[118:121], v[224:227], v[80:95]
	v_cvt_pk_bf16_f32 v100, v229, v230
	v_cvt_pk_bf16_f32 v101, v231, v232
	v_cvt_pk_bf16_f32 v102, v234, v235
	v_cvt_pk_bf16_f32 v103, v236, v237
	s_nop 0
	v_permlane32_swap_b32_e32 v100, v102
	v_permlane32_swap_b32_e32 v101, v103
	s_waitcnt lgkmcnt(1)
	v_mfma_f32_32x32x16_bf16 v[64:79], v[212:215], v[96:99], v[64:79]
	s_waitcnt lgkmcnt(0)
	v_mfma_f32_32x32x16_bf16 v[80:95], v[216:219], v[96:99], v[80:95]
	v_cvt_pk_bf16_f32 v96, v238, v239
	v_cvt_pk_bf16_f32 v97, v240, v241
	v_cvt_pk_bf16_f32 v98, v242, v243
	v_cvt_pk_bf16_f32 v99, v244, v245
	s_nop 0
	v_permlane32_swap_b32_e32 v96, v98
	v_permlane32_swap_b32_e32 v97, v99
	ds_read_b64_tr_b16 v[110:111], v188 offset:18432
	ds_read_b64_tr_b16 v[108:109], v188 offset:16384
	ds_read_b64_tr_b16 v[118:119], v188 offset:16896
	ds_read_b64_tr_b16 v[122:123], v188 offset:17408
	ds_read_b64_tr_b16 v[208:209], v188 offset:17920
	ds_read_b64_tr_b16 v[120:121], v188 offset:18944
	ds_read_b64_tr_b16 v[124:125], v188 offset:19456
	ds_read_b64_tr_b16 v[210:211], v188 offset:19968
	s_waitcnt lgkmcnt(6)
	v_mfma_f32_32x32x16_bf16 v[0:15], v[112:115], v[108:111], v[0:15]
	s_waitcnt lgkmcnt(2)
	v_mfma_f32_32x32x16_bf16 v[48:63], v[112:115], v[118:121], v[48:63]
	v_max_f32_e32 v108, v65, v65
	v_max_f32_e32 v109, v64, v64
	v_max_f32_e32 v108, v109, v108
	v_max3_f32 v108, v108, v66, v67
	v_max3_f32 v108, v108, v68, v69
	v_max3_f32 v108, v108, v70, v71
	v_max3_f32 v108, v108, v72, v73
	v_max3_f32 v108, v108, v74, v75
	v_max3_f32 v108, v108, v76, v77
	v_max3_f32 v118, v108, v78, v79
	s_waitcnt lgkmcnt(1)
	v_mfma_f32_32x32x16_bf16 v[32:47], v[112:115], v[122:125], v[32:47]
	ds_read_b64_tr_b16 v[108:109], v188 offset:20480
	ds_read_b64_tr_b16 v[110:111], v188 offset:22528
	ds_read_b64_tr_b16 v[122:123], v188 offset:23040
	ds_read_b64_tr_b16 v[120:121], v188 offset:20992
	s_waitcnt lgkmcnt(4)
	v_mfma_f32_32x32x16_bf16 v[16:31], v[112:115], v[208:211], v[16:31]
	v_max3_f32 v112, v118, v80, v81
	v_max3_f32 v112, v112, v82, v83
	v_max3_f32 v112, v112, v84, v85
	v_max3_f32 v112, v112, v86, v87
	v_max3_f32 v112, v112, v88, v89
	v_max3_f32 v112, v112, v90, v91
	v_max3_f32 v112, v112, v92, v93
	v_max3_f32 v112, v112, v94, v95
	v_mov_b32_e32 v113, v112
	s_nop 1
	v_permlane32_swap_b32_e32 v112, v113
	v_max_f32_e32 v113, v113, v113
	v_max_f32_e32 v112, v112, v112
	v_max_f32_e32 v118, v112, v113
	s_waitcnt lgkmcnt(2)
	v_mfma_f32_32x32x16_bf16 v[0:15], v[104:107], v[108:111], v[0:15]
	ds_read_b64_tr_b16 v[112:113], v188 offset:21504
	ds_read_b64_tr_b16 v[114:115], v188 offset:23552
	ds_read_b64_tr_b16 v[110:111], v188 offset:24064
	ds_read_b64_tr_b16 v[108:109], v188 offset:22016
	s_waitcnt lgkmcnt(4)
	v_mfma_f32_32x32x16_bf16 v[48:63], v[104:107], v[120:123], v[48:63]
	v_cmp_ge_f32_e32 vcc, s67, v118
	s_cmp_eq_u64 vcc, exec
	v_mov_b32_e32 v205, 1.0
	s_cbranch_scc0 .LBB0_669
; #define SBAR() __builtin_amdgcn_sched_barrier(0)
; #define DMAK(t, s) do { dc.gk = (unsigned)((size_t)(t) * TILEB); dc.kd = K_lds + (s) * SHM_K; dma_piece<0>(dc); dma_piece<1>(dc); dma_piece<2>(dc); } while (0)
; template <int G> __device__ __forceinline__ void v_load(s16x4& la, s16x4& ha, s16x4& lb, s16x4& hb, const __attribute__((address_space(3))) char* vb) {
;   constexpr int ks = G >> 1, d0 = (G & 1) * 2;
;   la = __builtin_amdgcn_ds_read_tr16_b64_v4i16((lds_s16x4b*)(vb + v_rd_off(d0, ks, 0))); ha = __builtin_amdgcn_ds_read_tr16_b64_v4i16((lds_s16x4b*)(vb + v_rd_off(d0, ks, 1)));
;   lb = __builtin_amdgcn_ds_read_tr16_b64_v4i16((lds_s16x4b*)(vb + v_rd_off(d0 + 1, ks, 0))); hb = __builtin_amdgcn_ds_read_tr16_b64_v4i16((lds_s16x4b*)(vb + v_rd_off(d0 + 1, ks, 1)));
; }
; template <int G> __device__ __forceinline__ void h2_stage(f32x16* o, f32x16& pc0, f32x16& pc1, float& m_reg, float& alC, SMState& st, bf16x8 pa0, bf16x8 pa1, bf16x8 pa2, bf16x8 pa3, ...
;   constexpr int ks = G >> 1, d0 = (G & 1) * 2;
;   s16x4 nla, nha, nlb, nhb;
;   if constexpr (G < 7) v_load<G + 1>(nla, nha, nlb, nhb, vb);
;   const bf16x8 pa = ks == 0 ? pa0 : ks == 1 ? pa1 : ks == 2 ? pa2 : pa3;
;     ...
;   o[d0] = __builtin_amdgcn_mfma_f32_32x32x16_bf16(pa, PK(la, ha), o[d0], 0, 0, 0);
;   o[d0 + 1] = __builtin_amdgcn_mfma_f32_32x32x16_bf16(pa, PK(lb, hb), o[d0 + 1], 0, 0, 0);
;     ...
;   SBAR(); ps_chunk<G>(pc0, pc1, m_reg, alC, st); SBAR();
;   if constexpr (G < 7) h2_stage<G + 1>(o, pc0, pc1, m_reg, alC, st, pa0, pa1, pa2, pa3, nla, nha, nlb, nhb, vb);
; }
; __device__ __forceinline__ void attn_body(const bf16_t* __restrict__ Qb, const bf16_t* __restrict__ KVb, int hcol, bf16_t* __restrict__ Ob, float* __restrict__ rsqa, int seq, char* lds) {
;     ...
;   f32x16 pA0, pA1, pB0, pB1; float alA, alB; bf16x8 pa0, pa1, pa2, pa3; SMState st; const int NT = seq / KVBLK;
;   DMAK(0, 0); DMAV(0, 0); DMAK(1, 1);
;   asm volatile("s_waitcnt vmcnt(3)" ::: "memory"); BAR();
;   qkt(pA0, pA1, K_lds, qr, qlds, kb); partialSM0(pA0, pA1, m_reg); alA = 1.f;
;   asm volatile("s_waitcnt vmcnt(0)" ::: "memory"); BAR();
;   int sc = 1;
;   for (int j = 1; j + 1 < NT; j += 2) {
;     STEP(pB0, pB1, alB, pA0, pA1, alA, j, sc, 0);
;     sc = NEXT3(sc);
;     STEP(pA0, pA1, alA, pB0, pB1, alB, j + 1, sc, 1);
;     sc = NEXT3(sc);
;   }
.LBB0_662:
	v_exp_f32_e32 v64, v64
	v_exp_f32_e32 v65, v65
	s_waitcnt lgkmcnt(2)
	v_mfma_f32_32x32x16_bf16 v[32:47], v[104:107], v[112:115], v[32:47]
	ds_read_b64_tr_b16 v[112:113], v188 offset:24576
	ds_read_b64_tr_b16 v[114:115], v188 offset:26624
	ds_read_b64_tr_b16 v[120:121], v188 offset:27136
	ds_read_b64_tr_b16 v[118:119], v188 offset:25088
	s_waitcnt lgkmcnt(4)
	v_mfma_f32_32x32x16_bf16 v[16:31], v[104:107], v[108:111], v[16:31]
	v_exp_f32_e32 v66, v66
	v_exp_f32_e32 v67, v67
	v_exp_f32_e32 v68, v68
	s_waitcnt lgkmcnt(2)
	v_mfma_f32_32x32x16_bf16 v[0:15], v[100:103], v[112:115], v[0:15]
	ds_read_b64_tr_b16 v[104:105], v188 offset:25600
	ds_read_b64_tr_b16 v[106:107], v188 offset:27648
	ds_read_b64_tr_b16 v[110:111], v188 offset:28160
	ds_read_b64_tr_b16 v[108:109], v188 offset:26112
	s_waitcnt lgkmcnt(4)
	v_mfma_f32_32x32x16_bf16 v[48:63], v[100:103], v[118:121], v[48:63]
	v_exp_f32_e32 v69, v69
	v_exp_f32_e32 v70, v70
	v_exp_f32_e32 v71, v71
	s_waitcnt lgkmcnt(2)
	v_mfma_f32_32x32x16_bf16 v[32:47], v[100:103], v[104:107], v[32:47]
	ds_read_b64_tr_b16 v[104:105], v188 offset:28672
	ds_read_b64_tr_b16 v[106:107], v188 offset:30720
	ds_read_b64_tr_b16 v[114:115], v188 offset:31232
	ds_read_b64_tr_b16 v[112:113], v188 offset:29184
	s_waitcnt lgkmcnt(4)
	v_mfma_f32_32x32x16_bf16 v[16:31], v[100:103], v[108:111], v[16:31]
	v_exp_f32_e32 v72, v72
	v_exp_f32_e32 v73, v73
	v_exp_f32_e32 v74, v74
	s_waitcnt lgkmcnt(2)
	v_mfma_f32_32x32x16_bf16 v[0:15], v[96:99], v[104:107], v[0:15]
	ds_read_b64_tr_b16 v[100:101], v188 offset:29696
	ds_read_b64_tr_b16 v[102:103], v188 offset:31744
	ds_read_b64_tr_b16 v[106:107], v188 offset:32256
	ds_read_b64_tr_b16 v[104:105], v188 offset:30208
	s_waitcnt lgkmcnt(4)
	v_mfma_f32_32x32x16_bf16 v[48:63], v[96:99], v[112:115], v[48:63]
	v_exp_f32_e32 v75, v75
	v_exp_f32_e32 v76, v76
	v_exp_f32_e32 v77, v77
	s_waitcnt lgkmcnt(0)
	v_exp_f32_e32 v78, v78
	v_exp_f32_e32 v79, v79
	s_waitcnt vmcnt(0)
	v_cmp_gt_f32_e32 vcc, 1.0, v205
	s_cbranch_vccz .Lattn_n2
	v_mfma_f32_32x32x16_bf16 v[32:47], v[96:99], v[100:103], v[32:47]
	v_mfma_f32_32x32x16_bf16 v[16:31], v[96:99], v[104:107], v[16:31]
	s_nop 15
	s_nop 15
	s_and_saveexec_b64 s[10:11], s[4:5]
	ds_write_b32 v189, v205 offset:128
	s_or_b64 exec, exec, s[10:11]
	s_waitcnt lgkmcnt(0)
	v_add_u32_e32 v108, s1, v166
	ds_read_b128 v[96:99], v108 offset:224
	ds_read_b128 v[100:103], v108 offset:192
	ds_read_b128 v[104:107], v108 offset:160
	ds_read_b128 v[108:111], v108 offset:128
	s_waitcnt lgkmcnt(3)
	v_pk_mul_f32 v[12:13], v[12:13], v[96:97]
	s_waitcnt lgkmcnt(2)
	v_pk_mul_f32 v[8:9], v[8:9], v[100:101]
	s_waitcnt lgkmcnt(1)
	v_pk_mul_f32 v[4:5], v[4:5], v[104:105]
	v_pk_mul_f32 v[14:15], v[14:15], v[98:99]
	v_pk_mul_f32 v[10:11], v[10:11], v[102:103]
	v_pk_mul_f32 v[6:7], v[6:7], v[106:107]
	s_waitcnt lgkmcnt(0)
	v_pk_mul_f32 v[2:3], v[2:3], v[110:111]
	v_pk_mul_f32 v[0:1], v[0:1], v[108:109]
	v_pk_mul_f32 v[60:61], v[60:61], v[96:97]
	v_pk_mul_f32 v[56:57], v[56:57], v[100:101]
	v_pk_mul_f32 v[52:53], v[52:53], v[104:105]
	v_pk_mul_f32 v[62:63], v[62:63], v[98:99]
	v_pk_mul_f32 v[58:59], v[58:59], v[102:103]
	v_pk_mul_f32 v[54:55], v[54:55], v[106:107]
	v_pk_mul_f32 v[50:51], v[50:51], v[110:111]
	v_pk_mul_f32 v[48:49], v[48:49], v[108:109]
	v_pk_mul_f32 v[44:45], v[44:45], v[96:97]
	v_pk_mul_f32 v[40:41], v[40:41], v[100:101]
	v_pk_mul_f32 v[36:37], v[36:37], v[104:105]
	v_pk_mul_f32 v[46:47], v[46:47], v[98:99]
	v_pk_mul_f32 v[42:43], v[42:43], v[102:103]
	v_pk_mul_f32 v[38:39], v[38:39], v[106:107]
	v_pk_mul_f32 v[34:35], v[34:35], v[110:111]
	v_pk_mul_f32 v[32:33], v[32:33], v[108:109]
	v_pk_mul_f32 v[28:29], v[28:29], v[96:97]
	v_pk_mul_f32 v[24:25], v[24:25], v[100:101]
	v_pk_mul_f32 v[20:21], v[20:21], v[104:105]
	v_pk_mul_f32 v[30:31], v[30:31], v[98:99]
	v_pk_mul_f32 v[26:27], v[26:27], v[102:103]
	v_pk_mul_f32 v[22:23], v[22:23], v[106:107]
	v_pk_mul_f32 v[18:19], v[18:19], v[110:111]
	v_pk_mul_f32 v[16:17], v[16:17], v[108:109]
	v_add_f32_e32 v243, v203, v204
	v_fmac_f32_e32 v243, v190, v202
	v_add_f32_e32 v190, v116, v117
	v_fmac_f32_e32 v190, v243, v206
	v_mov_b32_e32 v202, v205
	s_add_i32 s51, s51, 0x84000
	s_add_i32 s72, s72, 2
	s_mul_i32 s98, s73, 0x6000
	v_add_u32_e32 v203, s98, v193
	s_waitcnt lgkmcnt(0)
	s_barrier
	s_cmp_ge_u32 s72, s37
	s_cbranch_scc1 .LBB0_670
	ds_read_b128 v[204:207], v203 offset:32768
	ds_read_b128 v[208:211], v203 offset:45056
	s_add_i32 s10, s73, 1
	s_cmp_lg_u32 s73, 2
	s_cselect_b32 s52, s10, 0
	s_mov_b32 s10, s98
	s_branch .Lattn_m2
.Lattn_n2:
	v_add_f32_e32 v243, v203, v204
	v_fmac_f32_e32 v243, v190, v202
	v_add_f32_e32 v190, v116, v117
	v_fmac_f32_e32 v190, v243, v206
	v_mov_b32_e32 v202, v205
	s_add_i32 s51, s51, 0x84000
	s_add_i32 s72, s72, 2
	s_mul_i32 s98, s73, 0x6000
	v_add_u32_e32 v203, s98, v193
	s_waitcnt lgkmcnt(0)
	s_barrier
	s_cmp_ge_u32 s72, s37
	s_cbranch_scc1 .Lattn_tdef
	ds_read_b128 v[204:207], v203 offset:32768
	ds_read_b128 v[208:211], v203 offset:45056
	v_mfma_f32_32x32x16_bf16 v[32:47], v[96:99], v[100:103], v[32:47]
	v_mfma_f32_32x32x16_bf16 v[16:31], v[96:99], v[104:107], v[16:31]
	s_add_i32 s10, s73, 1
	s_cmp_lg_u32 s73, 2
	s_cselect_b32 s52, s10, 0
	s_mov_b32 s10, s98
	s_branch .Lattn_m2

; #define SBAR() __builtin_amdgcn_sched_barrier(0)
; #define DMAV(t, s) do { dc.gv = (unsigned)((size_t)(t) * TILEB); dc.vd = V_lds + (s) * SHM_V; dma_piece<3>(dc); dma_piece<4>(dc); } while (0)
; __device__ __forceinline__ void attn_body(const bf16_t* __restrict__ Qb, const bf16_t* __restrict__ KVb, int hcol, bf16_t* __restrict__ Ob, float* __restrict__ rsqa, int seq, char* lds) {
;     ...
;   for (int j = 1; j + 1 < NT; j += 2) {
;     STEP(pB0, pB1, alB, pA0, pA1, alA, j, sc, 0);
;     sc = NEXT3(sc);
;     STEP(pA0, pA1, alA, pB0, pB1, alB, j + 1, sc, 1);
;     sc = NEXT3(sc);
;   }
;   DMAV(NT - 1, 1);
;   SBAR(); qkt(pB0, pB1, K_lds + sc * SHM_K, qr, qlds, kb);
;   finishSM(pA0, pA1, alA, l_reg, pa0, pa1, pa2, pa3);
.Lattn_tdef:
	v_mfma_f32_32x32x16_bf16 v[32:47], v[96:99], v[100:103], v[32:47]
	v_mfma_f32_32x32x16_bf16 v[16:31], v[96:99], v[104:107], v[16:31]

; __global__ void __launch_bounds__(512, 2) fwd_megakernel(Params p) {
;     extern __shared__ __attribute__((aligned(16))) unsigned char lds[];
;     cg::grid_group grid = cg::this_grid();
	.amdhsa_kernel _Z14fwd_megakernel6Params
		.amdhsa_group_segment_fixed_size 0
		.amdhsa_private_segment_fixed_size 0
		.amdhsa_kernarg_size 488
		.amdhsa_user_sgpr_count 2
		.amdhsa_user_sgpr_dispatch_ptr 0
		.amdhsa_user_sgpr_queue_ptr 0
		.amdhsa_user_sgpr_kernarg_segment_ptr 1
		.amdhsa_user_sgpr_dispatch_id 0
		.amdhsa_user_sgpr_kernarg_preload_length 0
		.amdhsa_user_sgpr_kernarg_preload_offset 0
		.amdhsa_user_sgpr_private_segment_size 0
		.amdhsa_uses_dynamic_stack 0
		.amdhsa_enable_private_segment 0
		.amdhsa_system_sgpr_workgroup_id_x 1
		.amdhsa_system_sgpr_workgroup_id_y 0
		.amdhsa_system_sgpr_workgroup_id_z 0
		.amdhsa_system_sgpr_workgroup_info 0
		.amdhsa_system_vgpr_workitem_id 2
		.amdhsa_next_free_vgpr 247
		.amdhsa_next_free_sgpr 99
		.amdhsa_accum_offset 248
		.amdhsa_reserve_vcc 1
		.amdhsa_float_round_mode_32 0
		.amdhsa_float_round_mode_16_64 0
		.amdhsa_float_denorm_mode_32 3
		.amdhsa_float_denorm_mode_16_64 3
		.amdhsa_dx10_clamp 1
		.amdhsa_ieee_mode 1
		.amdhsa_fp16_overflow 0
		.amdhsa_tg_split 0
		.amdhsa_exception_fp_ieee_invalid_op 0
		.amdhsa_exception_fp_denorm_src 0
		.amdhsa_exception_fp_ieee_div_zero 0
		.amdhsa_exception_fp_ieee_overflow 0
		.amdhsa_exception_fp_ieee_underflow 0
		.amdhsa_exception_fp_ieee_inexact 0
		.amdhsa_exception_int_div_zero 0
	.end_amdhsa_kernel

; __global__ void __launch_bounds__(512, 2) fwd_megakernel(Params p) {
;     extern __shared__ __attribute__((aligned(16))) unsigned char lds[];
;     cg::grid_group grid = cg::this_grid();
amdhsa.kernels:
  - .agpr_count:     0
    .args:
      - .offset:         0
        .size:           232
        .value_kind:     by_value
      - .offset:         232
        .size:           4
        .value_kind:     hidden_block_count_x
      - .offset:         236
        .size:           4
        .value_kind:     hidden_block_count_y
      - .offset:         240
        .size:           4
        .value_kind:     hidden_block_count_z
      - .offset:         244
        .size:           2
        .value_kind:     hidden_group_size_x
      - .offset:         246
        .size:           2
        .value_kind:     hidden_group_size_y
      - .offset:         248
        .size:           2
        .value_kind:     hidden_group_size_z
      - .offset:         250
        .size:           2
        .value_kind:     hidden_remainder_x
      - .offset:         252
        .size:           2
        .value_kind:     hidden_remainder_y
      - .offset:         254
        .size:           2
        .value_kind:     hidden_remainder_z
      - .offset:         272
        .size:           8
        .value_kind:     hidden_global_offset_x
      - .offset:         280
        .size:           8
        .value_kind:     hidden_global_offset_y
      - .offset:         288
        .size:           8
        .value_kind:     hidden_global_offset_z
      - .offset:         296
        .size:           2
        .value_kind:     hidden_grid_dims
      - .offset:         320
        .size:           8
        .value_kind:     hidden_multigrid_sync_arg
      - .offset:         352
        .size:           4
        .value_kind:     hidden_dynamic_lds_size
    .group_segment_fixed_size: 0
    .kernarg_segment_align: 8
    .kernarg_segment_size: 488
    .language:       OpenCL C
    .language_version:
      - 2
      - 0
    .max_flat_workgroup_size: 512
    .name:           _Z14fwd_megakernel6Params
    .private_segment_fixed_size: 0
    .sgpr_count:     105
    .sgpr_spill_count: 63
    .symbol:         _Z14fwd_megakernel6Params.kd
    .uniform_work_group_size: 1
    .uses_dynamic_stack: false
    .vgpr_count:     247
    .vgpr_spill_count: 0
    .wavefront_size: 64
